# stack: one-hop seams + phase-start staging hoist + sink-logit load hoisted + hand-written SwiGLU epilogues
# speedup vs baseline: 1.0060x; 1.0060x over previous
; #define LAS __attribute__((address_space(3)))
; __device__ __forceinline__ void attn_item(const Args& a, LAS unsigned char* lds, int item, int tid, int wave, int lane) {
;     const int qb = item & 31, kvh = (item >> 5) & 1, b = item >> 6;
;     const int q0 = qb * 64;
;     const bf16_t* P = (const bf16_t*)(a.ws + WS_ACT);
;     const float* rope = (const float*)(a.ws + WS_ROPE);
;     bf16_t* HO = (bf16_t*)(a.ws + WS_HO);
;     LAS bf16_t* KS = (LAS bf16_t*)(lds + AT_KS); LAS bf16_t* VT = (LAS bf16_t*)(lds + AT_VT); LAS bf16_t* QS = (LAS bf16_t*)(lds + AT_QS);
;     LAS bf16_t* PS = (LAS bf16_t*)(lds + AT_PS) + wave * 16 * VP;
;     const int fr = lane & 15, fq = lane >> 4;
;     const size_t rowbase = (size_t)b * SEQ;
;     const int grp = tid & 3;
;     u32x4 kk[2][2], vv[2][2], qq[2][2]; f32x4 tk[2][4], tq[2][4];
; #pragma unroll
;     for (int it = 0; it < 2; ++it) {
;         const int t = tid + 512 * it;
;         const int kc = (t >> 2) < 192 ? (t >> 2) : 191, kpos = q0 - 128 + kc, kposc = kpos < 0 ? 0 : kpos;
;         const bf16_t* kp = P + (rowbase + kposc) * NIN + PC_KA + kvh * 64 + grp * 16; kk[it][0] = *(const u32x4*)kp; kk[it][1] = *(const u32x4*)(kp + 8);
;         const bf16_t* vp = P + (rowbase + kposc) * NIN + PC_VA + kvh * 64 + grp * 16; vv[it][0] = *(const u32x4*)vp; vv[it][1] = *(const u32x4*)(vp + 8);
;         const float* tkp = rope + (rowbase + kposc) * 16;
; #pragma unroll
;         for (int q = 0; q < 4; ++q) tk[it][q] = *(const f32x4*)(tkp + 4 * q);
;         const int qi = (t >> 2) & 63, gq = t >> 8;
;         const size_t row = rowbase + q0 + qi;
;         const bf16_t* qp = P + row * NIN + PC_QA + (kvh * 4 + gq) * 64 + grp * 16; qq[it][0] = *(const u32x4*)qp; qq[it][1] = *(const u32x4*)(qp + 8);
;         const float* tqp = rope + row * 16;
; #pragma unroll
;         for (int q = 0; q < 4; ++q) tq[it][q] = *(const f32x4*)(tqp + 4 * q);
;     }
;     ...
;     const int g = wave >> 1;
;     const float sink = a.sinks[kvh * 4 + g];
.LBB0_1088:
	s_lshl_b32 s22, s43, 5
	s_add_i32 s22, s22, s81
	s_and_b32 s30, s22, 0xffffffc0
	s_add_i32 s30, s30, s0
	s_or_b32 s31, s30, s22
	s_lshl_b32 s37, s31, 6
	s_and_b32 s36, s37, 0x7c0
	s_ashr_i32 s30, s30, 6
	s_add_i32 s45, s36, 0xffffff80
	s_ashr_i32 s31, s30, 31
	v_add_u32_e32 v0, s45, v93
	s_lshl_b64 s[30:31], s[30:31], 11
	v_max_i32_e32 v0, 0, v0
	v_mov_b32_e32 v1, v2
	v_lshl_add_u64 v[0:1], s[30:31], 0, v[0:1]
	s_bfe_u32 s44, s22, 0x10005
	s_lshl_b32 s84, s44, 2
	s_add_i32 s84, s84, s33
	s_lshl_b32 s84, s84, 2
	v_mov_b32_e32 v154, s84
	global_load_dword v155, v154, s[62:63]
	v_mad_u64_u32 v[4:5], s[34:35], v0, s39, v[86:87]
	v_mad_i32_i24 v5, v1, s39, v5
	s_lshl_b32 s22, s44, 7
	v_lshl_add_u64 v[4:5], v[4:5], 0, s[22:23]
	v_lshl_add_u64 v[4:5], v[4:5], 0, v[88:89]
	v_add_u32_e32 v22, s45, v95
	v_mov_b32_e32 v23, v2
	v_add_co_u32_e32 v8, vcc, s40, v4
	v_lshl_add_u64 v[22:23], s[30:31], 0, v[22:23]
	v_lshl_add_u64 v[6:7], v[4:5], 0, s[24:25]
	v_addc_co_u32_e32 v9, vcc, 0, v5, vcc
	v_lshl_add_u64 v[4:5], v[4:5], 0, s[26:27]
	v_or_b32_e32 v3, s36, v85
	v_mad_u64_u32 v[24:25], s[34:35], v22, s39, v[86:87]
	s_lshl_b32 s46, s44, 8
	global_load_dwordx4 v[80:83], v[8:9], off
	global_load_dwordx4 v[76:79], v[6:7], off offset:16
	global_load_dwordx4 v[72:75], v[8:9], off offset:256
	global_load_dwordx4 v[68:71], v[4:5], off offset:16
	v_or_b32_e32 v4, s30, v3
	v_mad_i32_i24 v25, v23, s39, v25
	v_mad_u64_u32 v[20:21], s[34:35], v4, s39, v[86:87]
	v_or_b32_e32 v3, s46, v94
	v_lshl_add_u64 v[24:25], v[24:25], 0, s[22:23]
	v_mov_b32_e32 v5, s31
	v_mad_i32_i24 v21, s31, v104, v21
	v_lshlrev_b32_e32 v6, 1, v3
	v_mov_b32_e32 v7, v2
	v_lshl_add_u64 v[24:25], v[24:25], 0, v[88:89]
	v_lshl_add_u64 v[6:7], v[20:21], 0, v[6:7]
	v_lshlrev_b64 v[4:5], 6, v[4:5]
	v_add_co_u32_e32 v28, vcc, s40, v24
	v_lshlrev_b64 v[22:23], 6, v[22:23]
	v_lshl_add_u64 v[6:7], v[6:7], 0, v[88:89]
	v_lshl_add_u64 v[16:17], s[20:21], 0, v[4:5]
	v_addc_co_u32_e32 v29, vcc, 0, v25, vcc
	v_lshl_add_u64 v[22:23], s[20:21], 0, v[22:23]
	global_load_dwordx4 v[60:63], v[6:7], off offset:3088
	global_load_dwordx4 v[64:67], v[6:7], off offset:3072
	s_nop 0
	global_load_dwordx4 v[4:7], v[16:17], off offset:48
	global_load_dwordx4 v[12:15], v[16:17], off offset:32
	s_waitcnt lgkmcnt(0)
	global_load_dwordx4 v[8:11], v[16:17], off offset:16
	s_nop 0
	global_load_dwordx4 v[16:19], v[16:17], off
	v_lshl_add_u64 v[26:27], v[24:25], 0, s[24:25]
	global_load_dwordx4 v[40:43], v[28:29], off
	global_load_dwordx4 v[36:39], v[26:27], off offset:16
	v_lshl_add_u64 v[24:25], v[24:25], 0, s[26:27]
	global_load_dwordx4 v[32:35], v[28:29], off offset:256
	s_nop 0
	global_load_dwordx4 v[28:31], v[24:25], off offset:16
	global_load_dwordx4 v[44:47], v[22:23], off offset:48
	global_load_dwordx4 v[52:55], v[22:23], off offset:32
	global_load_dwordx4 v[48:51], v[22:23], off offset:16
	global_load_dwordx4 v[56:59], v[22:23], off
	v_add_lshl_u32 v22, s46, v96, 1
	v_mov_b32_e32 v23, v2
	v_lshl_add_u64 v[20:21], v[20:21], 0, v[22:23]
	v_lshl_add_u64 v[24:25], v[20:21], 0, v[88:89]
	global_load_dwordx4 v[20:23], v[24:25], off offset:3088
	s_nop 0
	global_load_dwordx4 v[24:27], v[24:25], off offset:3072
	s_and_saveexec_b64 s[34:35], s[8:9]
	s_cbranch_execnz .LBB0_1105
	s_or_b64 exec, exec, s[34:35]
	v_cmp_le_i32_e32 vcc, s36, v97
	s_and_saveexec_b64 s[34:35], vcc
	s_cbranch_execnz .LBB0_1106

; #define LAS __attribute__((address_space(3)))
; __device__ __forceinline__ unsigned cvt_pk_bf16(float lo, float hi) { unsigned r; asm volatile("v_cvt_pk_bf16_f32 %0, %1, %2" : "=v"(r) : "v"(lo), "v"(hi)); return r; }
; __device__ __forceinline__ void attn_item(const Args& a, LAS unsigned char* lds, int item, int tid, int wave, int lane) {
;     ...
;             for (int q = 0; q < 4; ++q) { o0[q] = cvt_pk_bf16(x[2 * q] * 0.125f, x[2 * q + 1] * 0.125f); o1[q] = cvt_pk_bf16(x[8 + 2 * q] * 0.125f, x[8 + 2 * q + 1] * 0.125f); }
;             *(LAS u32x4*)(QS + (gq * 64 + qi) * LP + grp * 16) = o0; *(LAS u32x4*)(QS + (gq * 64 + qi) * LP + grp * 16 + 8) = o1;
;         }
;     }
;     __syncthreads();
;     const int g = wave >> 1;
;     const float sink = a.sinks[kvh * 4 + g];
;     constexpr float LOG2E = 1.4426950408889634f;
; #pragma unroll 1
;     for (int rr = 0; rr < 2; ++rr) {
;         const int rt = 2 * (wave & 1) + rr;
;         const bf16x8 bq0 = *(const LAS bf16x8*)(QS + (g * 64 + 16 * rt + fr) * LP + 8 * fq), bq1 = *(const LAS bf16x8*)(QS + (g * 64 + 16 * rt + fr) * LP + 32 + 8 * fq);
.LBB0_1100:
	s_or_b64 exec, exec, s[34:35]
	v_mul_f32_e32 v4, 0x3e000000, v37
	v_mul_f32_e32 v0, 0x3e000000, v0
	v_mul_f32_e32 v3, 0x3e000000, v36
	v_cvt_pk_bf16_f32 v4, v3, v4
	v_mul_f32_e32 v1, 0x3e000000, v1
	v_cvt_pk_bf16_f32 v8, v0, v1
	v_mul_f32_e32 v0, 0x3e000000, v34
	v_mul_f32_e32 v1, 0x3e000000, v35
	v_cvt_pk_bf16_f32 v5, v0, v1
	v_mul_f32_e32 v0, 0x3e000000, v24
	v_mul_f32_e32 v1, 0x3e000000, v25
	v_cvt_pk_bf16_f32 v9, v0, v1
	v_mul_f32_e32 v0, 0x3e000000, v32
	v_mul_f32_e32 v1, 0x3e000000, v33
	v_cvt_pk_bf16_f32 v6, v0, v1
	v_mul_f32_e32 v0, 0x3e000000, v28
	s_lshl_b32 s22, s44, 2
	v_mul_f32_e32 v1, 0x3e000000, v29
	v_cvt_pk_bf16_f32 v10, v0, v1
	v_mul_f32_e32 v0, 0x3e000000, v30
	s_add_i32 s22, s22, s33
	v_mul_f32_e32 v1, 0x3e000000, v31
	v_cvt_pk_bf16_f32 v7, v0, v1
	v_mul_f32_e32 v0, 0x3e000000, v20
	s_lshl_b32 s34, s22, 2
	v_mul_f32_e32 v1, 0x3e000000, v21
	v_cvt_pk_bf16_f32 v11, v0, v1
	v_mov_b32_e32 v0, s34
	ds_write_b128 v106, v[4:7] offset:53248
	ds_write_b128 v106, v[8:11] offset:53264
	s_waitcnt lgkmcnt(0)
	s_barrier
	v_mov_b32_e32 v40, v155
	v_and_b32_e32 v1, 64, v107
	v_xor_b32_e32 v0, 16, v107
	v_add_u32_e32 v1, 64, v1
	v_cmp_lt_i32_e32 vcc, v0, v1
	s_cmpk_lt_u32 s36, 0x80
	s_cselect_b64 s[34:35], -1, 0
	v_cndmask_b32_e32 v0, v107, v0, vcc
	v_lshlrev_b32_e32 v41, 2, v0
	v_xor_b32_e32 v0, 32, v107
	v_cmp_lt_i32_e32 vcc, v0, v1
	s_or_b32 s37, s37, 0xffffff80
	s_lshl_b32 s22, s22, 6
	v_cndmask_b32_e32 v0, v107, v0, vcc
	s_mov_b32 s45, 0
	v_lshlrev_b32_e32 v42, 2, v0
	s_sub_i32 s44, 0, s37
	v_or_b32_e32 v43, s36, v92
	s_mov_b64 s[36:37], -1
	s_lshl_b32 s22, s22, 1
	s_waitcnt vmcnt(0)
	s_cmp_eq_u32 s43, 3
	s_cbranch_scc1 .Lapf_skip
	s_add_i32 s32, s43, 1
	s_lshl_b32 s32, s32, 5
	s_add_i32 s32, s32, s81
	s_bfe_u32 s53, s32, 0x10005
	s_lshr_b32 s54, s32, 6
	s_lshl_b32 s55, s92, 1
	s_add_i32 s54, s54, s55
	s_lshl_b32 s54, s54, 11
	s_lshl_b32 s55, s81, 6
	s_add_i32 s70, s54, s55
	s_add_i32 s71, s55, 0xffffff80
	s_lshl_b32 s79, s53, 7
	s_add_i32 s79, s79, 0x1000
	s_lshl_b32 s80, s53, 9
	s_add_i32 s80, s80, 0xc00
	s_movk_i32 s82, 0x2400
	s_movk_i32 s83, 0xc0
	v_add_u32_e32 v148, s71, v153
	v_max_i32_e32 v148, 0, v148
	v_add_u32_e32 v148, s54, v148
	v_mul_lo_u32 v148, v148, s82
	v_add_u32_e32 v148, s79, v148
	v_subrev_u32_e32 v149, s83, v153
	v_min_u32_e32 v149, 0xff, v149
	v_lshrrev_b32_e32 v150, 2, v149
	v_and_b32_e32 v149, 3, v149
	v_add_u32_e32 v150, s70, v150
	v_mul_lo_u32 v150, v150, s82
	v_lshl_add_u32 v150, v149, 7, v150
	v_add_u32_e32 v150, s80, v150
	v_cmp_gt_u32_e64 s[66:67], s83, v153
	s_nop 1
	v_cndmask_b32_e64 v148, v150, v148, s[66:67]
	global_load_dword v151, v148, s[68:69]
	global_load_dword v151, v148, s[68:69] offset:256
